# v73: v68 + PEER base priority chosen by the CU census (first workgroup on a CU keeps priority 1, the second 0) instead of lq parity, so the two co-resident workgroups always differ
# baseline (speedup 1.0000x reference)
.LBB0_852:
	s_or_b64 exec, exec, s[0:1]
	v_readlane_b32 s0, v255, 62
	s_nop 0
	s_cmp_eq_u32 s0, -1
	s_cbranch_scc1 .Lpb_parity_a
	s_cmp_eq_u32 s0, 0x7fff
	s_cbranch_scc1 .LBB0_854
	s_setprio 1
	s_branch .LBB0_854
.Lpb_parity_a:
	v_readlane_b32 s0, v254, 28
	s_nop 0
	s_bitcmp0_b32 s0, 0
	s_cbranch_scc1 .LBB0_854
	s_setprio 1

.LBB0_869:
	ds_read2st64_b32 v[4:5], v220 offset0:12 offset1:13
	ds_read2st64_b32 v[6:7], v220 offset0:14 offset1:15
	v_mov_b32_e32 v10, 0
	v_mov_b32_e32 v11, 0
	s_mov_b32 s0, 0
	s_waitcnt lgkmcnt(0)
	v_lshrrev_b32_e32 v8, 11, v4
	v_lshrrev_b32_e32 v9, 11, v5
	v_cmp_eq_u32_e64 s[42:43], 0, v8
	v_cmp_eq_u32_e64 s[100:101], 0, v9
	s_bcnt1_i32_b64 s1, s[42:43]
	s_bcnt1_i32_b64 s41, s[100:101]
	v_mbcnt_lo_u32_b32 v12, s42, 0
	v_mbcnt_hi_u32_b32 v12, s43, v12
	v_mbcnt_lo_u32_b32 v13, s100, 0
	v_mbcnt_hi_u32_b32 v13, s101, v13
	s_add_i32 s98, s0, s1
	v_add_u32_e32 v12, s0, v12
	v_add_u32_e32 v13, s98, v13
	v_cndmask_b32_e64 v10, v10, v12, s[42:43]
	v_cndmask_b32_e64 v11, v11, v13, s[100:101]
	s_add_i32 s0, s98, s41
	v_cmp_eq_u32_e64 s[42:43], 1, v8
	v_cmp_eq_u32_e64 s[100:101], 1, v9
	s_bcnt1_i32_b64 s1, s[42:43]
	s_bcnt1_i32_b64 s41, s[100:101]
	v_mbcnt_lo_u32_b32 v12, s42, 0
	v_mbcnt_hi_u32_b32 v12, s43, v12
	v_mbcnt_lo_u32_b32 v13, s100, 0
	v_mbcnt_hi_u32_b32 v13, s101, v13
	s_add_i32 s98, s0, s1
	v_add_u32_e32 v12, s0, v12
	v_add_u32_e32 v13, s98, v13
	v_cndmask_b32_e64 v10, v10, v12, s[42:43]
	v_cndmask_b32_e64 v11, v11, v13, s[100:101]
	s_add_i32 s0, s98, s41
	v_cmp_eq_u32_e64 s[42:43], 2, v8
	v_cmp_eq_u32_e64 s[100:101], 2, v9
	s_bcnt1_i32_b64 s1, s[42:43]
	s_bcnt1_i32_b64 s41, s[100:101]
	v_mbcnt_lo_u32_b32 v12, s42, 0
	v_mbcnt_hi_u32_b32 v12, s43, v12
	v_mbcnt_lo_u32_b32 v13, s100, 0
	v_mbcnt_hi_u32_b32 v13, s101, v13
	s_add_i32 s98, s0, s1
	v_add_u32_e32 v12, s0, v12
	v_add_u32_e32 v13, s98, v13
	v_cndmask_b32_e64 v10, v10, v12, s[42:43]
	v_cndmask_b32_e64 v11, v11, v13, s[100:101]
	s_add_i32 s0, s98, s41
	v_cmp_eq_u32_e64 s[42:43], 3, v8
	v_cmp_eq_u32_e64 s[100:101], 3, v9
	s_bcnt1_i32_b64 s1, s[42:43]
	s_bcnt1_i32_b64 s41, s[100:101]
	v_mbcnt_lo_u32_b32 v12, s42, 0
	v_mbcnt_hi_u32_b32 v12, s43, v12
	v_mbcnt_lo_u32_b32 v13, s100, 0
	v_mbcnt_hi_u32_b32 v13, s101, v13
	s_add_i32 s98, s0, s1
	v_add_u32_e32 v12, s0, v12
	v_add_u32_e32 v13, s98, v13
	v_cndmask_b32_e64 v10, v10, v12, s[42:43]
	v_cndmask_b32_e64 v11, v11, v13, s[100:101]
	s_add_i32 s0, s98, s41
	v_cmp_eq_u32_e64 s[42:43], 4, v8
	v_cmp_eq_u32_e64 s[100:101], 4, v9
	s_bcnt1_i32_b64 s1, s[42:43]
	s_bcnt1_i32_b64 s41, s[100:101]
	v_mbcnt_lo_u32_b32 v12, s42, 0
	v_mbcnt_hi_u32_b32 v12, s43, v12
	v_mbcnt_lo_u32_b32 v13, s100, 0
	v_mbcnt_hi_u32_b32 v13, s101, v13
	s_add_i32 s98, s0, s1
	v_add_u32_e32 v12, s0, v12
	v_add_u32_e32 v13, s98, v13
	v_cndmask_b32_e64 v10, v10, v12, s[42:43]
	v_cndmask_b32_e64 v11, v11, v13, s[100:101]
	s_add_i32 s0, s98, s41
	v_cmp_eq_u32_e64 s[42:43], 5, v8
	v_cmp_eq_u32_e64 s[100:101], 5, v9
	s_bcnt1_i32_b64 s1, s[42:43]
	s_bcnt1_i32_b64 s41, s[100:101]
	v_mbcnt_lo_u32_b32 v12, s42, 0
	v_mbcnt_hi_u32_b32 v12, s43, v12
	v_mbcnt_lo_u32_b32 v13, s100, 0
	v_mbcnt_hi_u32_b32 v13, s101, v13
	s_add_i32 s98, s0, s1
	v_add_u32_e32 v12, s0, v12
	v_add_u32_e32 v13, s98, v13
	v_cndmask_b32_e64 v10, v10, v12, s[42:43]
	v_cndmask_b32_e64 v11, v11, v13, s[100:101]
	s_add_i32 s0, s98, s41
	v_cmp_eq_u32_e64 s[42:43], 6, v8
	v_cmp_eq_u32_e64 s[100:101], 6, v9
	s_bcnt1_i32_b64 s1, s[42:43]
	s_bcnt1_i32_b64 s41, s[100:101]
	v_mbcnt_lo_u32_b32 v12, s42, 0
	v_mbcnt_hi_u32_b32 v12, s43, v12
	v_mbcnt_lo_u32_b32 v13, s100, 0
	v_mbcnt_hi_u32_b32 v13, s101, v13
	s_add_i32 s98, s0, s1
	v_add_u32_e32 v12, s0, v12
	v_add_u32_e32 v13, s98, v13
	v_cndmask_b32_e64 v10, v10, v12, s[42:43]
	v_cndmask_b32_e64 v11, v11, v13, s[100:101]
	s_add_i32 s0, s98, s41
	v_cmp_eq_u32_e64 s[42:43], 7, v8
	v_cmp_eq_u32_e64 s[100:101], 7, v9
	s_bcnt1_i32_b64 s1, s[42:43]
	s_bcnt1_i32_b64 s41, s[100:101]
	v_mbcnt_lo_u32_b32 v12, s42, 0
	v_mbcnt_hi_u32_b32 v12, s43, v12
	v_mbcnt_lo_u32_b32 v13, s100, 0
	v_mbcnt_hi_u32_b32 v13, s101, v13
	s_add_i32 s98, s0, s1
	v_add_u32_e32 v12, s0, v12
	v_add_u32_e32 v13, s98, v13
	v_cndmask_b32_e64 v10, v10, v12, s[42:43]
	v_cndmask_b32_e64 v11, v11, v13, s[100:101]
	s_add_i32 s0, s98, s41
	s_and_b32 s1, s19, 1
	s_mul_i32 s1, s1, 0x7f
	v_xor_b32_e32 v10, s1, v10
	v_xor_b32_e32 v11, s1, v11
	v_lshl_add_u32 v10, v10, 2, v199
	v_lshl_add_u32 v11, v11, 2, v199
	ds_write_b32 v10, v4
	ds_write_b32 v11, v5
	ds_write_b32 v10, v6 offset:512
	ds_write_b32 v11, v7 offset:512
	v_add_u32_e32 v0, s48, v0
	v_cmp_gt_i32_e32 vcc, s52, v0
	v_mov_b32_e32 v2, s49
	v_mov_b32_e32 v3, s50
	v_cndmask_b32_e32 v2, v2, v3, vcc
	v_add_u32_e32 v152, v0, v2
	v_ashrrev_i32_e32 v153, 31, v152
	v_lshlrev_b64 v[2:3], 11, v[152:153]
	v_lshl_add_u64 v[2:3], v[138:139], 0, v[2:3]
	global_load_dwordx2 v[4:5], v[2:3], off
	global_load_dwordx2 v[6:7], v[2:3], off offset:512
	global_load_dwordx2 v[10:11], v[2:3], off offset:1024
	global_load_dwordx2 v[12:13], v[2:3], off offset:1536
	s_lshl_b32 s0, s19, 10
	v_add3_u32 v9, v131, s0, v136
	ds_read2st64_b32 v[14:15], v220 offset0:12 offset1:13
	ds_read2st64_b32 v[16:17], v220 offset0:14 offset1:15
	v_mov_b32_e32 v184, 0
	s_mov_b32 s1, 0
	v_mov_b32_e32 v185, v184
	v_mov_b32_e32 v186, v184
	v_mov_b32_e32 v187, v184
	v_mov_b32_e32 v182, v184
	v_mov_b32_e32 v183, v184
	v_mov_b32_e32 v180, v184
	v_mov_b32_e32 v181, v184
	v_mov_b32_e32 v178, v184
	v_mov_b32_e32 v179, v184
	v_mov_b32_e32 v176, v184
	v_mov_b32_e32 v177, v184
	v_mov_b32_e32 v174, v184
	v_mov_b32_e32 v175, v184
	v_mov_b32_e32 v172, v184
	v_mov_b32_e32 v173, v184
	s_waitcnt lgkmcnt(0)
	v_mov_b32_e32 v0, v14
	v_lshlrev_b64 v[18:19], 2, v[0:1]
	v_lshl_add_u64 v[20:21], s[34:35], 0, v[18:19]
	v_lshl_add_u64 v[18:19], s[90:91], 0, v[18:19]
	global_load_dword v8, v[20:21], off
	global_load_dword v22, v[18:19], off
	v_mov_b32_e32 v0, v15
	v_lshlrev_b64 v[18:19], 2, v[0:1]
	v_lshl_add_u64 v[20:21], s[34:35], 0, v[18:19]
	v_lshl_add_u64 v[18:19], s[90:91], 0, v[18:19]
	global_load_dword v23, v[20:21], off
	global_load_dword v24, v[18:19], off
	s_waitcnt vmcnt(0)
	v_lshlrev_b32_e32 v154, 16, v4
	v_and_b32_e32 v155, 0xffff0000, v4
	v_lshlrev_b32_e32 v156, 16, v5
	v_and_b32_e32 v157, 0xffff0000, v5
	v_lshlrev_b32_e32 v158, 16, v6
	v_and_b32_e32 v159, 0xffff0000, v6
	v_lshlrev_b32_e32 v162, 16, v7
	v_and_b32_e32 v163, 0xffff0000, v7
	v_lshlrev_b32_e32 v164, 16, v10
	v_and_b32_e32 v165, 0xffff0000, v10
	v_lshlrev_b32_e32 v166, 16, v11
	v_and_b32_e32 v167, 0xffff0000, v11
	v_lshlrev_b32_e32 v168, 16, v12
	v_and_b32_e32 v169, 0xffff0000, v12
	v_lshlrev_b32_e32 v170, 16, v13
	v_and_b32_e32 v171, 0xffff0000, v13
	v_mul_f32_e32 v6, v16, v22
	v_mul_f32_e32 v0, v17, v24
	ds_write2st64_b32 v9, v8, v23 offset1:1
	ds_write2st64_b32 v9, v6, v0 offset0:2 offset1:3
	v_readlane_b32 s98, v255, 62
	s_nop 0
	s_cmp_eq_u32 s98, -1
	s_cbranch_scc1 .Lprio_base_par
	s_cmp_eq_u32 s98, 0x7fff
	s_cbranch_scc1 .Lprio_base_zero
	s_branch .Lprio_base_one
.Lprio_base_par:
	v_readlane_b32 s98, v254, 28
	s_nop 0
	s_bitcmp1_b32 s98, 0
	s_cbranch_scc1 .Lprio_base_one
.Lprio_base_zero:
	s_setprio 0
	s_branch .Lprio_base_done
